# seam 0: cooperative-groups grid.sync replaced by the XCD-hierarchical barrier used at the other seams (plus v2 tile remap)
# speedup vs baseline: 1.0173x; 1.0173x over previous
; __device__ __forceinline__ int tid_() { int t = threadIdx.x; asm volatile("" : "+v"(t)); return t; }
; __device__ __forceinline__ unsigned xb_ld(unsigned* p)              { return __hip_atomic_load(p, __ATOMIC_RELAXED, __HIP_MEMORY_SCOPE_AGENT); }
; __device__ __forceinline__ void xcd_barrier_complete(unsigned* bar, unsigned x, unsigned& nloc, unsigned& nx) {
;     const unsigned G = gridDim.x * gridDim.y * gridDim.z;
;     unsigned sum, cnt, mine, sp = 0u;
;     for (;;) {
;         sum = 0u; cnt = 0u; mine = 0u;
; #pragma unroll
;         for (unsigned j = 0; j < 16; ++j) { const unsigned c = xb_ld(&bar[XB_XCNT(j)]); sum += c; cnt += (c > 0u) ? 1u : 0u; mine = (j == x) ? c : mine; }
;         if (sum == G) break;
;         __builtin_amdgcn_s_sleep(1);
;         if ((++sp & 255u) == 0u) { if (xb_ld(&bar[XB_TMO])) break; if (sp > XB_SPIN_CAP) { atomicAdd(&bar[XB_TMO], 1u); break; } }
;     }
;     nloc = mine > 0u ? mine : 1u; nx = cnt > 0u ? cnt : 1u;
; }
; __device__ __forceinline__ void xcd_barrier(const XcdBarrier& b) {
;     asm volatile("s_waitcnt vmcnt(0)" ::: "memory");
;     __syncthreads();
;     if (tid_() == 0) {
;         unsigned* bar = b.bar;
;         __builtin_amdgcn_s_waitcnt(0);
;         unsigned nloc = b.st[0], nx = b.st[1];
;         if (nloc == 0u) { xcd_barrier_complete(bar, b.x, nloc, nx); b.st[0] = nloc; b.st[1] = nx; }
.LBB0_58:
	v_readlane_b32 s6, v228, 12
	v_readlane_b32 s7, v228, 13
	s_cmp_lt_i32 s7, 2
	s_cbranch_scc1 .LBB0_70
	s_getreg_b32 s2, hwreg(HW_REG_XCC_ID, 0, 4)
	s_waitcnt vmcnt(0)
	v_mov_b32_e32 v0, v220
	s_waitcnt vmcnt(0) lgkmcnt(0)
	s_barrier
	s_nop 0
	v_cmp_eq_u32_e32 vcc, 0, v0
	s_and_saveexec_b64 s[0:1], vcc
	s_cbranch_execz .Lxs0_139
	v_mov_b32_e32 v0, 0
	s_waitcnt vmcnt(0) expcnt(0) lgkmcnt(0)
	ds_read_b32 v2, v0 offset:57344
	ds_read_b32 v1, v0 offset:57348
	s_and_b32 s33, s2, 15
	s_waitcnt lgkmcnt(1)
	v_cmp_ne_u32_e32 vcc, 0, v2
	s_cbranch_vccnz .Lxs0_103
	v_readlane_b32 s2, v228, 10
	v_readlane_b32 s3, v228, 11
	v_readlane_b32 s4, v228, 14
	v_readlane_b32 s36, v228, 2
	s_mul_i32 s44, s3, s4
	v_readlane_b32 s42, v228, 8
	s_mul_i32 s44, s44, s2
	v_readlane_b32 s43, v228, 9
	s_add_u32 s2, s42, 0x179ed200
	s_addc_u32 s3, s43, 0
	s_add_u32 s4, s42, 0x179ed400
	s_addc_u32 s5, s43, 0
	s_add_u32 s6, s42, 0x179ed500
	s_addc_u32 s7, s43, 0
	s_add_u32 s8, s42, 0x179ed600
	s_addc_u32 s9, s43, 0
	s_add_u32 s10, s42, 0x179ed700
	s_addc_u32 s11, s43, 0
	s_add_u32 s12, s42, 0x179ed800
	s_addc_u32 s13, s43, 0
	s_add_u32 s14, s42, 0x179ed900
	s_addc_u32 s15, s43, 0
	s_add_u32 s16, s42, 0x179eda00
	s_addc_u32 s17, s43, 0
	s_add_u32 s18, s42, 0x179edb00
	s_addc_u32 s19, s43, 0
	s_add_u32 s20, s42, 0x179edc00
	s_addc_u32 s21, s43, 0
	s_add_u32 s22, s42, 0x179edd00
	s_addc_u32 s23, s43, 0
	s_add_u32 s24, s42, 0x179ede00
	s_addc_u32 s25, s43, 0
	s_add_u32 s26, s42, 0x179edf00
	s_addc_u32 s27, s43, 0
	s_add_u32 s28, s42, 0x179ee000
	s_addc_u32 s29, s43, 0
	s_add_u32 s30, s42, 0x179ee100
	s_addc_u32 s31, s43, 0
	s_add_u32 s34, s42, 0x179ee200
	s_addc_u32 s35, s43, 0
	v_readlane_b32 s37, v228, 3
	s_add_u32 s36, s42, 0x179ee300
	s_addc_u32 s37, s43, 0
	s_mov_b32 s45, 1
	v_readlane_b32 s38, v228, 4
	v_readlane_b32 s39, v228, 5
	v_readlane_b32 s40, v228, 6
	v_readlane_b32 s41, v228, 7
	s_branch .Lxs0_91

; __device__ __forceinline__ int tid_() { int t = threadIdx.x; asm volatile("" : "+v"(t)); return t; }
; __device__ __forceinline__ unsigned xb_ld(unsigned* p)              { return __hip_atomic_load(p, __ATOMIC_RELAXED, __HIP_MEMORY_SCOPE_AGENT); }
; __device__ __forceinline__ unsigned xb_add(unsigned* p, unsigned v) { return __hip_atomic_fetch_add(p, v, __ATOMIC_RELAXED, __HIP_MEMORY_SCOPE_AGENT); }
; __device__ void ph_gemm1(const P& p, u16* lds) {
;   const int wid = tid_() >> 6, wm = wid >> 1, wn = wid & 1;
;   const int NT = 23, NTILES = 264 * NT;
;   int it = blockIdx.x;
;   if (it >= NTILES) return;
;   auto ops = [&](int t) __attribute__((always_inline)) { return gemm_ops(p_Abf + (size_t)(t / NT) * 128 * DM, DM, p_WinT + (size_t)(t % NT) * 128 * DM, DM); };
;   GemmOps g = ops(it);
;   __syncthreads();
;   gemm_prologue(g, lds);
; __device__ __forceinline__ void xcd_barrier(const XcdBarrier& b) {
;     asm volatile("s_waitcnt vmcnt(0)" ::: "memory");
;     __syncthreads();
;     if (tid_() == 0) {
;         unsigned* bar = b.bar;
;         __builtin_amdgcn_s_waitcnt(0);
;         unsigned nloc = b.st[0], nx = b.st[1];
;         if (nloc == 0u) { xcd_barrier_complete(bar, b.x, nloc, nx); b.st[0] = nloc; b.st[1] = nx; }
;         const unsigned old = xb_add(&bar[XB_XSUB(b.x)], 1u);
;         const unsigned gen = old / nloc;
;         if (old + 1u == (gen + 1u) * nloc) {
;             __builtin_amdgcn_fence(__ATOMIC_RELEASE, "agent");
;             asm volatile("s_waitcnt vmcnt(0)" ::: "memory");
;             const unsigned og = xb_add(&bar[XB_TOP], 1u);
;             const unsigned tg = og / nx;
;             if (og + 1u == (tg + 1u) * nx) xb_add(&bar[XB_TOPGEN], 1u);
;             else XB_SPIN(xb_ld(&bar[XB_TOPGEN]) == tg, bar);
;             __builtin_amdgcn_fence(__ATOMIC_ACQUIRE, "agent");
;             xb_add(&bar[XB_XGEN(b.x)], 1u);
;             asm volatile("s_waitcnt vmcnt(0)" ::: "memory");
;         } else {
;             XB_SPIN(xb_ld(&bar[XB_XGEN(b.x)]) == gen, bar);
;             __builtin_amdgcn_fence(__ATOMIC_ACQUIRE, "agent");
;             asm volatile("s_waitcnt vmcnt(0)" ::: "memory");
;         }
;     }
;     __syncthreads();
; }
.Lxs0_139:
	s_or_b64 exec, exec, s[0:1]
	v_readlane_b32 s6, v228, 12
	v_readlane_b32 s7, v228, 13
	s_waitcnt lgkmcnt(0)
	s_barrier
.LBB0_70:
	s_cmp_lt_i32 s6, 2
	s_cselect_b64 s[0:1], -1, 0
	s_cmp_gt_i32 s7, 1
	s_cselect_b64 s[2:3], -1, 0
	s_and_b64 s[0:1], s[0:1], s[2:3]
	s_andn2_b64 vcc, exec, s[0:1]
	s_cbranch_vccnz .LBB0_140
	v_readlane_b32 s0, v228, 0
	v_mov_b32_e32 v0, v220
	s_cmpk_gt_i32 s0, 0x17b7
	v_readlane_b32 s1, v228, 1
	s_cbranch_scc1 .LBB0_86
	v_readlane_b32 s0, v228, 2
	v_readlane_b32 s6, v228, 8
	v_readlane_b32 s8, v228, 0
	s_and_b32 s81, s8, 7
	s_lshr_b32 s82, s8, 3
	s_mul_hi_u32 s83, s82, 0x1642c86
	s_mul_i32 s84, s83, 184
	s_sub_u32 s84, s82, s84
	s_cmp_lt_u32 s83, 4
	s_cselect_b32 s85, 3, 0
	s_cselect_b32 s86, 7, 0
	s_lshr_b32 s87, s84, s85
	s_and_b32 s84, s84, s86
	s_lshl_b32 s83, s83, 3
	s_add_u32 s83, s83, s84
	s_mul_i32 s81, s81, 33
	s_add_u32 s81, s81, s83
	s_mul_i32 s81, s81, 23
	s_add_u32 s80, s81, s87
	v_readlane_b32 s7, v228, 9
	s_add_u32 s12, s6, 0x3f40000
	s_mul_hi_i32 s0, s80, 0xb21642c9
	v_readlane_b32 s1, v228, 3
	s_addc_u32 s13, s7, 0
	s_add_i32 s0, s0, s80
	s_lshr_b32 s1, s0, 31
	s_ashr_i32 s0, s0, 4
	s_add_i32 s0, s0, s1
	v_readlane_b32 s2, v228, 4
	v_readlane_b32 s3, v228, 5
	s_ashr_i32 s1, s0, 31
	s_lshl_b64 s[2:3], s[0:1], 18
	s_add_u32 s2, s12, s2
	s_mul_i32 s0, s0, 23
	v_mov_b32_e32 v1, v220
	v_mov_b32_e32 v2, v220
	s_addc_u32 s3, s13, s3
	s_sub_i32 s0, s80, s0
	s_ashr_i32 s1, s0, 31
	v_lshrrev_b32_e32 v5, 4, v1
	v_lshrrev_b32_e32 v3, 2, v1
	v_ashrrev_i32_e32 v2, 2, v2
	v_xor_b32_e32 v1, v5, v1
	s_lshl_b64 s[0:1], s[0:1], 18
	v_bfi_b32 v2, -16, v2, v3
	v_lshlrev_b32_e32 v1, 4, v1
	s_add_u32 s0, s6, s0
	v_add_u32_e32 v4, 64, v2
	v_ashrrev_i32_e32 v3, 31, v2
	v_and_b32_e32 v64, 48, v1
	v_mov_b32_e32 v1, v220
	s_addc_u32 s1, s7, s1
	v_lshlrev_b64 v[2:3], 11, v[2:3]
	v_ashrrev_i32_e32 v5, 31, v4
	s_barrier
	v_lshl_add_u64 v[6:7], s[2:3], 0, v[2:3]
	v_mov_b32_e32 v65, 0
	v_lshlrev_b64 v[4:5], 11, v[4:5]
	v_lshl_add_u64 v[2:3], s[0:1], 0, v[2:3]
	v_lshlrev_b32_e32 v1, 4, v1
	v_lshl_add_u64 v[70:71], v[2:3], 0, v[64:65]
	v_lshl_add_u64 v[2:3], s[0:1], 0, v[4:5]
	v_and_b32_e32 v1, 0xfffffc00, v1
	v_lshl_add_u64 v[72:73], v[2:3], 0, v[64:65]
	v_readfirstlane_b32 s0, v1
	v_add_u32_e32 v2, 0x1000, v1
	v_lshl_add_u64 v[66:67], v[6:7], 0, v[64:65]
	v_lshl_add_u64 v[6:7], s[2:3], 0, v[4:5]
	s_mov_b32 m0, s0
	v_readfirstlane_b32 s0, v2
	v_add_u32_e32 v2, 0x2000, v1
	v_lshl_add_u64 v[68:69], v[6:7], 0, v[64:65]
	global_load_lds_dwordx4 v[66:67], off
	s_mov_b32 m0, s0
	v_readfirstlane_b32 s0, v2
	v_add_u32_e32 v1, 0x3000, v1
	global_load_lds_dwordx4 v[68:69], off
	s_mov_b32 m0, s0
	v_readfirstlane_b32 s0, v1
	global_load_lds_dwordx4 v[70:71], off
	s_mov_b32 m0, s0
	v_mov_b32_e32 v1, v220
	global_load_lds_dwordx4 v[72:73], off
	v_lshl_add_u64 v[2:3], v[66:67], 0, 64
	v_lshlrev_b32_e32 v1, 4, v1
	v_and_b32_e32 v1, 0xfffffc00, v1
	v_add_u32_e32 v4, 0x4000, v1
	v_and_b32_e32 v74, 64, v0
	v_readfirstlane_b32 s0, v4
	v_add_u32_e32 v4, 0x5000, v1
	s_mov_b32 m0, s0
	v_readfirstlane_b32 s0, v4
	v_add_u32_e32 v4, 0x6000, v1
	global_load_lds_dwordx4 v[2:3], off
	v_lshl_add_u64 v[2:3], v[68:69], 0, 64
	s_mov_b32 m0, s0
	v_readfirstlane_b32 s0, v4
	v_add_u32_e32 v1, 0x7000, v1
	global_load_lds_dwordx4 v[2:3], off
	v_lshl_add_u64 v[2:3], v[70:71], 0, 64
	s_mov_b32 m0, s0
	v_readfirstlane_b32 s0, v1
	global_load_lds_dwordx4 v[2:3], off
	v_lshl_add_u64 v[2:3], v[72:73], 0, 64
	s_mov_b32 m0, s0
	v_ashrrev_i32_e32 v0, 1, v0
	global_load_lds_dwordx4 v[2:3], off
	v_readlane_b32 s4, v228, 6
	v_readlane_b32 s5, v228, 7
	v_and_b32_e32 v75, 0xffffffc0, v0
	s_add_u32 s0, s6, 0x8140000
	v_or_b32_e32 v76, 16, v75
	v_or_b32_e32 v77, 20, v75
	v_or_b32_e32 v78, 24, v75
	v_or_b32_e32 v79, 28, v75
	v_or_b32_e32 v80, 32, v75
	v_or_b32_e32 v81, 36, v75
	v_or_b32_e32 v82, 40, v75
	v_or_b32_e32 v83, 44, v75
	v_or_b32_e32 v84, 48, v75
	v_or_b32_e32 v85, 52, v75
	v_or_b32_e32 v86, 56, v75
	v_or_b32_e32 v87, 60, v75
	s_addc_u32 s1, s7, 0
	s_mov_b32 s14, 0x3ffffc0
	s_movk_i32 s15, 0x13c0
	s_mov_b64 s[2:3], 0x80
	s_mov_b64 s[4:5], 0xc0
	s_mov_b64 s[6:7], 0x100
	s_movk_i32 s16, 0x1100
	s_movk_i32 s17, 0x440
	s_movk_i32 s18, 0xb10
	s_movk_i32 s19, 0x110
	s_movk_i32 s20, 0x1620
	s_mov_b32 s21, s8
	v_readlane_b32 s9, v228, 1
	s_branch .LBB0_74
